# v51 + GEMM phase prologues: K-tile-1 stage loads issued before the first wait (two cold round trips overlap)
# baseline (speedup 1.0000x reference)
.LBB0_298:
	s_add_u32 s16, s64, 0x49000000
	s_addc_u32 s17, s65, 0
	s_add_u32 s20, s64, 0x200000
	s_addc_u32 s21, s65, 0
	s_add_u32 s22, s64, 0x280000
	v_readlane_b32 s24, v255, 5
	s_addc_u32 s23, s65, 0
	s_bfe_u32 s28, s24, 0x20006
	s_mov_b64 s[24:25], 0x80
	s_add_i32 m0, s43, 0x18000
	v_lshl_add_u64 v[10:11], v[10:11], 0, s[24:25]
	s_lshl_b32 s62, s18, 6
	s_lshl_b32 s18, s18, 13
	s_lshl_b32 s30, s28, 5
	s_lshl_b32 s29, s28, 12
	global_load_lds_dwordx4 v[10:11], off
	v_lshl_add_u64 v[8:9], v[8:9], 0, s[24:25]
	s_add_i32 m0, s43, 0x1a000
	s_add_i32 s63, s43, 0x8000
	s_mov_b64 s[34:35], s[64:65]
	s_add_i32 s64, s43, 0xa000
	global_load_lds_dwordx4 v[8:9], off
	v_lshl_add_u64 v[4:5], v[4:5], 0, s[24:25]
	s_mov_b32 m0, s63
	s_add_u32 s26, s6, 0x80080
	global_load_lds_dwordx4 v[4:5], off
	v_lshl_add_u64 v[4:5], v[6:7], 0, s[24:25]
	s_mov_b32 m0, s64
	s_addc_u32 s27, s7, 0
	global_load_lds_dwordx4 v[4:5], off
	s_add_i32 m0, s43, 0x1c000
	v_lshl_add_u64 v[4:5], s[26:27], 0, v[196:197]
	global_load_lds_dwordx4 v[4:5], off
	v_lshl_add_u64 v[4:5], s[26:27], 0, v[198:199]
	s_add_i32 m0, s43, 0x1e000
	v_and_b32_e32 v1, 15, v2
	global_load_lds_dwordx4 v[4:5], off
	s_waitcnt vmcnt(8)
	s_barrier
	v_lshlrev_b32_e32 v7, 2, v2
	v_and_b32_e32 v4, 48, v2
	v_lshlrev_b32_e32 v6, 6, v1
	v_and_b32_e32 v7, 32, v7
	v_and_b32_e32 v5, 0x400, v18
	v_bitop3_b32 v4, v6, v7, v4 bitop3:0x36
	v_or3_b32 v6, v5, s18, v4
	v_or3_b32 v229, v5, s29, v4
	v_and_b32_e32 v5, 64, v2
	v_xor_b32_e32 v4, 1, v2
	v_add_u32_e32 v5, 64, v5
	v_cmp_lt_i32_e32 vcc, v4, v5
	v_lshrrev_b32_e32 v228, 4, v2
	s_lshl_b32 s65, s28, 7
	v_cndmask_b32_e32 v4, v2, v4, vcc
	v_lshlrev_b32_e32 v230, 2, v4
	v_xor_b32_e32 v4, 2, v2
	v_cmp_lt_i32_e32 vcc, v4, v5
	s_cmp_eq_u32 s28, 0
	v_readlane_b32 s18, v255, 0
	v_cndmask_b32_e32 v4, v2, v4, vcc
	v_lshlrev_b32_e32 v231, 2, v4
	v_xor_b32_e32 v4, 4, v2
	v_cmp_lt_i32_e32 vcc, v4, v5
	s_cselect_b64 s[28:29], -1, 0
	s_ashr_i32 s66, s86, 31
	v_cndmask_b32_e32 v4, v2, v4, vcc
	v_lshlrev_b32_e32 v232, 2, v4
	v_xor_b32_e32 v4, 8, v2
	v_cmp_lt_i32_e32 vcc, v4, v5
	s_ashr_i32 s67, s18, 31
	s_add_u32 s18, s34, s65
	v_cndmask_b32_e32 v2, v2, v4, vcc
	v_lshlrev_b32_e32 v233, 2, v2
	v_mov_b32_e32 v2, v194
	v_lshlrev_b64 v[2:3], 2, v[2:3]
	v_lshl_add_u64 v[202:203], s[2:3], 0, v[2:3]
	v_lshl_add_u64 v[204:205], s[8:9], 0, v[2:3]
	v_lshlrev_b32_e32 v2, 15, v12
	v_and_b32_e32 v2, 0xffff0000, v2
	v_lshl_add_u32 v2, v13, 12, v2
	v_and_b32_e32 v3, 1, v12
	v_lshl_or_b32 v2, v3, 6, v2
	v_lshl_add_u32 v206, v14, 1, v2
	v_lshlrev_b32_e32 v2, 15, v15
	s_addc_u32 s26, s35, 0
	v_and_b32_e32 v2, 0xffff0000, v2
	s_waitcnt vmcnt(6)
	s_add_u32 s68, s18, 0x90000
	v_readlane_b32 s34, v255, 51
	v_lshl_add_u32 v2, v16, 12, v2
	v_and_b32_e32 v3, 1, v15
	s_mov_b32 s27, 0
	s_addc_u32 s69, s26, 0
	v_readlane_b32 s35, v255, 52
	v_lshl_or_b32 v2, v3, 6, v2
	s_add_i32 s70, 0, 0x10000
	s_add_i32 s71, 0, 0x14000
	v_lshl_add_u64 v[200:201], v[194:195], 2, s[34:35]
	v_mov_b32_e32 v207, v195
	v_lshl_add_u32 v208, v17, 1, v2
	v_mov_b32_e32 v209, v195
	v_mov_b64_e32 v[210:211], 0x900
	v_mov_b64_e32 v[212:213], 0x8ff
	v_add_u32_e32 v234, s70, v229
	v_add_u32_e32 v235, s71, v229
	v_add_u32_e32 v236, 0, v6
	s_mov_b32 s72, 1.0
	v_mov_b32_e32 v237, 0x3727c5ac
	s_mov_b32 s73, 0xf800000
	v_mov_b32_e32 v238, 0x260
	s_lshl_b32 s26, s30, 1
	s_mov_b32 s18, s27
	s_barrier
	s_branch .LBB0_301

.LBB0_1222:
	s_add_u32 s6, s64, 0x410000
	s_addc_u32 s7, s65, 0
	s_add_u32 s8, s64, 0x312000
	v_readlane_b32 s10, v255, 48
	s_addc_u32 s9, s65, 0
	s_lshl_b32 s10, s10, 5
	s_and_b32 s57, s10, 0x60
	s_mov_b64 s[10:11], 0x80
	s_add_i32 m0, s19, 0x18000
	v_lshl_add_u64 v[8:9], v[8:9], 0, s[10:11]
	s_lshl_b32 s56, s1, 6
	s_lshl_b32 s1, s1, 13
	s_lshr_b32 s14, s57, 3
	global_load_lds_dwordx4 v[8:9], off
	v_lshl_add_u64 v[6:7], v[6:7], 0, s[10:11]
	s_add_i32 m0, s19, 0x1a000
	s_add_i32 s60, s19, 0x8000
	s_add_i32 s61, s19, 0xa000
	global_load_lds_dwordx4 v[6:7], off
	v_lshl_add_u64 v[2:3], v[2:3], 0, s[10:11]
	s_mov_b32 m0, s60
	s_add_u32 s12, s30, 0x80080
	global_load_lds_dwordx4 v[2:3], off
	v_lshl_add_u64 v[2:3], v[4:5], 0, s[10:11]
	s_mov_b32 m0, s61
	s_addc_u32 s13, s31, 0
	global_load_lds_dwordx4 v[2:3], off
	s_add_i32 m0, s19, 0x1c000
	v_lshl_add_u64 v[2:3], s[12:13], 0, v[168:169]
	global_load_lds_dwordx4 v[2:3], off
	v_lshl_add_u64 v[2:3], s[12:13], 0, v[172:173]
	s_add_i32 m0, s19, 0x1e000
	v_and_b32_e32 v1, 15, v12
	global_load_lds_dwordx4 v[2:3], off
	s_waitcnt vmcnt(8)
	s_barrier
	v_lshrrev_b32_e32 v2, 6, v12
	v_lshlrev_b32_e32 v6, 2, v12
	v_and_b32_e32 v3, 48, v12
	v_lshlrev_b32_e32 v4, 10, v2
	v_lshlrev_b32_e32 v5, 6, v1
	v_and_b32_e32 v6, 32, v6
	v_or_b32_e32 v2, s14, v2
	v_bitop3_b32 v7, v5, v6, v3 bitop3:0x36
	v_or_b32_e32 v3, v5, v3
	v_lshlrev_b32_e32 v2, 10, v2
	v_bitop3_b32 v193, v3, v2, v6 bitop3:0xde
	v_lshlrev_b32_e32 v2, 15, v10
	v_and_b32_e32 v2, 0xffff0000, v2
	v_lshl_add_u32 v2, v11, 12, v2
	v_and_b32_e32 v3, 1, v10
	v_lshl_or_b32 v2, v3, 6, v2
	v_lshl_add_u32 v174, v13, 1, v2
	v_lshlrev_b32_e32 v2, 15, v14
	s_sext_i32_i8 s65, s0
	v_readlane_b32 s0, v255, 5
	v_and_b32_e32 v2, 0xffff0000, v2
	s_waitcnt vmcnt(6)
	s_cmpk_lt_u32 s0, 0x100
	v_lshl_add_u32 v2, v15, 12, v2
	v_and_b32_e32 v3, 1, v14
	v_or3_b32 v4, v4, s1, v7
	s_cselect_b64 s[12:13], -1, 0
	v_lshl_or_b32 v2, v3, 6, v2
	s_add_i32 s63, 0, 0x10000
	s_add_i32 s64, 0, 0x14000
	v_lshrrev_b32_e32 v191, 4, v12
	s_ashr_i32 s62, s86, 31
	v_mov_b32_e32 v175, v169
	v_lshl_add_u32 v176, v16, 1, v2
	v_mov_b32_e32 v177, v169
	v_mov_b64_e32 v[180:181], 0x1ff
	v_add_u32_e32 v197, s63, v193
	v_add_u32_e32 v201, s64, v193
	v_add_u32_e32 v204, 0, v4
	s_barrier
	s_branch .LBB0_1225

.LBB0_1361:
	v_readlane_b32 s0, v255, 53
	v_readlane_b32 s1, v255, 54
	s_add_u32 s69, s0, 0x75000000
	s_addc_u32 s70, s1, 0
	v_and_b32_e32 v230, 15, v22
	v_lshrrev_b32_e32 v231, 4, v22
	v_and_b32_e32 v28, 48, v22
	v_lshlrev_b32_e32 v22, 2, v22
	s_add_u32 s71, s0, 0x75800000
	v_readlane_b32 s24, v255, 5
	v_lshlrev_b32_e32 v29, 6, v230
	v_and_b32_e32 v22, 32, v22
	s_mov_b64 s[22:23], 0x80
	s_addc_u32 s72, s1, 0
	s_bfe_u32 s8, s24, 0x20006
	s_lshl_b32 s0, s41, 13
	v_and_b32_e32 v27, 0x400, v27
	v_bitop3_b32 v22, v29, v22, v28 bitop3:0x36
	s_add_i32 m0, s65, 0x18000
	v_lshl_add_u64 v[14:15], v[14:15], 0, s[22:23]
	s_lshl_b32 s73, s41, 6
	v_or3_b32 v28, v27, s0, v22
	s_lshl_b32 s76, s8, 5
	s_lshl_b32 s0, s8, 12
	global_load_lds_dwordx4 v[14:15], off
	v_lshl_add_u64 v[12:13], v[12:13], 0, s[22:23]
	s_add_i32 m0, s65, 0x1a000
	s_add_i32 s77, s65, 0x8000
	s_add_i32 s78, s65, 0xa000
	v_or3_b32 v232, v27, s0, v22
	global_load_lds_dwordx4 v[12:13], off
	v_lshl_add_u64 v[10:11], v[10:11], 0, s[22:23]
	s_mov_b32 m0, s77
	s_add_u32 s0, s6, 0x80080
	global_load_lds_dwordx4 v[10:11], off
	v_lshl_add_u64 v[8:9], v[8:9], 0, s[22:23]
	s_mov_b32 m0, s78
	s_addc_u32 s1, s7, 0
	global_load_lds_dwordx4 v[8:9], off
	s_add_i32 m0, s65, 0x1c000
	v_lshl_add_u64 v[8:9], s[0:1], 0, v[144:145]
	global_load_lds_dwordx4 v[8:9], off
	v_lshl_add_u64 v[8:9], s[0:1], 0, v[148:149]
	s_add_i32 m0, s65, 0x1e000
	s_lshl_b32 s0, s41, 4
	global_load_lds_dwordx4 v[8:9], off
	s_waitcnt vmcnt(8)
	s_barrier
	s_lshl_b32 s1, s8, 2
	s_or_b32 s0, s1, s0
	s_lshl_b32 s85, s0, 3
	s_lshl_b32 s16, s0, 7
	s_or_b32 s20, s85, 8
	s_or_b32 s21, s85, 16
	s_or_b32 s46, s85, 24
	s_add_i32 s47, s85, 0x100
	s_add_i32 s83, s85, 0x108
	s_add_i32 s84, s85, 0x110
	s_addk_i32 s85, 0x118
	s_lshl_b32 s17, s8, 9
	s_cmpk_gt_u32 s24, 0xff
	s_cselect_b64 s[24:25], -1, 0
	s_cmp_lg_u32 s41, 1
	s_cselect_b64 s[0:1], -1, 0
	v_cndmask_b32_e64 v8, 0, 1, s[0:1]
	s_and_b64 s[0:1], s[0:1], exec
	s_cselect_b32 s1, 0, 2
	v_or_b32_e32 v8, s1, v8
	s_cselect_b32 s0, 0x800, 0
	v_lshlrev_b32_e32 v8, 11, v8
	s_add_i32 s92, 0, 0x20c00
	v_readlane_b32 s1, v255, 0
	v_lshl_add_u64 v[150:151], v[2:3], 2, s[2:3]
	v_add_u32_e32 v2, s92, v8
	v_and_b32_e32 v3, 1, v16
	s_ashr_i32 s90, s1, 31
	s_lshl_b32 s1, s41, 8
	v_add_u32_e32 v233, s17, v2
	v_add3_u32 v2, v18, v19, v20
	v_lshlrev_b32_e32 v3, 6, v3
	s_add_i32 s91, s1, 0
	v_lshl_or_b32 v2, v2, 12, v3
	v_and_b32_e32 v3, 1, v21
	s_ashr_i32 s87, s86, 31
	s_add_i32 s91, s91, 0x25400
	s_add_i32 s93, s92, s16
	s_lshl_b32 s1, s8, 7
	v_lshl_add_u64 v[152:153], v[6:7], 0, v[4:5]
	v_lshl_add_u32 v4, v17, 1, v2
	v_add3_u32 v2, v24, v25, v26
	v_lshlrev_b32_e32 v3, 6, v3
	s_mov_b64 s[18:19], 0x80080
	s_waitcnt vmcnt(6)
	s_add_u32 s94, s2, s1
	v_lshl_or_b32 v2, v2, 12, v3
	s_addc_u32 s95, s3, 0
	s_add_i32 s96, s92, s0
	v_lshl_add_u64 v[154:155], v[4:5], 0, s[18:19]
	v_lshl_add_u32 v4, v23, 1, v2
	s_add_i32 s97, 0, 0x10000
	s_add_i32 s0, 0, 0x14000
	s_mov_b32 s9, 0
	s_add_i32 s96, s96, s17
	v_lshl_add_u64 v[156:157], v[4:5], 0, s[18:19]
	v_mov_b64_e32 v[158:159], 0xe00
	v_mov_b64_e32 v[160:161], 0xdff
	v_add_u32_e32 v234, s97, v232
	v_add_u32_e32 v235, s0, v232
	v_add_u32_e32 v236, 0, v28
	s_mov_b32 s1, 0xe000
	v_mov_b32_e32 v237, 0x3727c5ac
	s_mov_b32 s16, 0xf800000
	v_mov_b32_e32 v238, 0x260
	s_mov_b32 s26, 0x3fb8aa3b
	s_mov_b32 s28, 0x3f317218
	s_movk_i32 s17, 0x7000
	s_barrier
	s_branch .LBB0_1364

.LBB0_1540:
	s_add_u32 s10, s64, 0x180000
	v_readlane_b32 s4, v255, 48
	s_addc_u32 s11, s65, 0
	s_lshl_b32 s4, s4, 5
	s_mov_b64 s[12:13], 0x80
	s_and_b32 s37, s4, 0x60
	s_add_i32 m0, s17, 0x18000
	v_lshl_add_u64 v[8:9], v[8:9], 0, s[12:13]
	s_lshl_b32 s36, s3, 6
	s_lshl_b32 s3, s3, 13
	s_lshr_b32 s14, s37, 3
	global_load_lds_dwordx4 v[8:9], off
	v_lshl_add_u64 v[6:7], v[6:7], 0, s[12:13]
	s_add_i32 m0, s17, 0x1a000
	s_add_i32 s38, s17, 0x8000
	s_add_i32 s39, s17, 0xa000
	global_load_lds_dwordx4 v[6:7], off
	v_lshl_add_u64 v[2:3], v[2:3], 0, s[12:13]
	s_mov_b32 m0, s38
	s_add_u32 s4, s26, 0x380080
	global_load_lds_dwordx4 v[2:3], off
	v_lshl_add_u64 v[2:3], v[4:5], 0, s[12:13]
	s_mov_b32 m0, s39
	s_addc_u32 s5, s27, 0
	global_load_lds_dwordx4 v[2:3], off
	s_add_i32 m0, s17, 0x1c000
	v_lshl_add_u64 v[2:3], s[4:5], 0, v[196:197]
	global_load_lds_dwordx4 v[2:3], off
	v_lshl_add_u64 v[2:3], s[4:5], 0, v[200:201]
	s_add_i32 m0, s17, 0x1e000
	v_and_b32_e32 v1, 15, v11
	global_load_lds_dwordx4 v[2:3], off
	s_waitcnt vmcnt(8)
	s_barrier
	v_lshrrev_b32_e32 v2, 6, v11
	v_lshlrev_b32_e32 v6, 2, v11
	v_and_b32_e32 v3, 48, v11
	v_lshlrev_b32_e32 v4, 10, v2
	v_lshlrev_b32_e32 v5, 6, v1
	v_and_b32_e32 v6, 32, v6
	v_or_b32_e32 v2, s14, v2
	v_bitop3_b32 v7, v5, v6, v3 bitop3:0x36
	v_or_b32_e32 v3, v5, v3
	v_lshlrev_b32_e32 v2, 10, v2
	v_bitop3_b32 v244, v3, v2, v6 bitop3:0xde
	v_and_b32_e32 v3, 64, v11
	v_xor_b32_e32 v2, 16, v11
	v_add_u32_e32 v3, 64, v3
	v_cmp_lt_i32_e32 vcc, v2, v3
	v_or3_b32 v4, v4, s3, v7
	v_readlane_b32 s3, v255, 5
	v_cndmask_b32_e32 v2, v11, v2, vcc
	v_lshlrev_b32_e32 v245, 2, v2
	v_xor_b32_e32 v2, 32, v11
	v_cmp_lt_i32_e32 vcc, v2, v3
	s_cmpk_lt_u32 s3, 0x100
	v_readlane_b32 s3, v255, 0
	v_cndmask_b32_e32 v2, v11, v2, vcc
	s_cselect_b64 s[14:15], -1, 0
	v_lshlrev_b32_e32 v246, 2, v2
	s_ashr_i32 s41, s3, 31
	v_lshrrev_b32_e32 v3, 1, v10
	v_mul_lo_u32 v2, v13, s2
	s_mov_b32 s3, 0x38000
	v_mad_u64_u32 v[2:3], s[22:23], v3, s3, v[2:3]
	v_or_b32_e32 v2, v2, v12
	s_mov_b64 s[4:5], 0x380080
	v_add_lshl_u32 v2, v2, v14, 1
	v_mov_b32_e32 v3, v197
	v_lshl_add_u64 v[202:203], v[2:3], 0, s[4:5]
	v_lshrrev_b32_e32 v3, 1, v15
	v_mul_lo_u32 v2, v16, s2
	v_mad_u64_u32 v[2:3], s[2:3], v3, s3, v[2:3]
	s_waitcnt vmcnt(6)
	v_or_b32_e32 v2, v2, v17
	v_add_lshl_u32 v2, v2, v18, 1
	v_mov_b32_e32 v3, v197
	s_add_i32 s42, 0, 0x10000
	s_add_i32 s43, 0, 0x14000
	v_lshrrev_b32_e32 v243, 4, v11
	s_ashr_i32 s40, s86, 31
	v_lshl_add_u64 v[204:205], v[2:3], 0, s[4:5]
	v_mov_b64_e32 v[206:207], 0x200
	v_mov_b64_e32 v[208:209], 0x1ff
	v_add_u32_e32 v247, s42, v244
	v_add_u32_e32 v248, s43, v244
	v_add_u32_e32 v249, 0, v4
	s_mov_b32 s56, 0x2f800000
	s_mov_b32 s57, 0xcf800000
	s_barrier
	s_branch .LBB0_1543

.LBB0_1637:
	s_add_u32 s48, s64, 0x180000
	s_addc_u32 s49, s65, 0
	s_add_u32 s24, s64, 0x1a0000
	v_readlane_b32 s2, v255, 48
	s_addc_u32 s25, s65, 0
	s_lshl_b32 s2, s2, 5
	s_mov_b64 s[26:27], 0x80
	s_and_b32 s4, s2, 0x60
	s_add_i32 m0, s39, 0x18000
	v_lshl_add_u64 v[8:9], v[8:9], 0, s[26:27]
	s_lshl_b32 s1, s0, 13
	s_lshr_b32 s5, s4, 3
	global_load_lds_dwordx4 v[8:9], off
	v_lshl_add_u64 v[6:7], v[6:7], 0, s[26:27]
	s_add_i32 m0, s39, 0x1a000
	s_add_i32 s71, s39, 0x8000
	s_add_i32 s72, s39, 0xa000
	global_load_lds_dwordx4 v[6:7], off
	v_lshl_add_u64 v[2:3], v[2:3], 0, s[26:27]
	s_mov_b32 m0, s71
	s_add_u32 s2, s18, 0x100080
	global_load_lds_dwordx4 v[2:3], off
	v_lshl_add_u64 v[2:3], v[4:5], 0, s[26:27]
	s_mov_b32 m0, s72
	s_addc_u32 s3, s19, 0
	global_load_lds_dwordx4 v[2:3], off
	s_add_i32 m0, s39, 0x1c000
	v_lshl_add_u64 v[2:3], s[2:3], 0, v[148:149]
	global_load_lds_dwordx4 v[2:3], off
	v_lshl_add_u64 v[2:3], s[2:3], 0, v[152:153]
	s_add_i32 m0, s39, 0x1e000
	v_lshrrev_b32_e32 v4, 6, v11
	global_load_lds_dwordx4 v[2:3], off
	s_waitcnt vmcnt(8)
	s_barrier
	v_and_b32_e32 v2, 15, v11
	v_lshrrev_b32_e32 v3, 1, v11
	v_lshlrev_b32_e32 v7, 2, v11
	v_lshl_or_b32 v1, s0, 6, v2
	v_and_b32_e32 v3, 56, v3
	v_and_b32_e32 v5, 48, v11
	v_lshlrev_b32_e32 v6, 10, v4
	v_lshlrev_b32_e32 v2, 6, v2
	v_and_b32_e32 v7, 32, v7
	v_or_b32_e32 v4, s5, v4
	v_bitop3_b32 v8, v2, v7, v5 bitop3:0x36
	v_or_b32_e32 v2, v2, v5
	v_lshlrev_b32_e32 v4, 10, v4
	v_add_u32_e32 v197, s4, v3
	v_and_b32_e32 v3, 64, v11
	v_bitop3_b32 v196, v2, v4, v7 bitop3:0xde
	v_xor_b32_e32 v2, 16, v11
	v_add_u32_e32 v3, 64, v3
	v_cmp_lt_i32_e32 vcc, v2, v3
	v_readlane_b32 s0, v255, 5
	s_waitcnt vmcnt(6)
	s_cmpk_lt_u32 s0, 0x100
	v_cndmask_b32_e32 v2, v11, v2, vcc
	v_lshlrev_b32_e32 v198, 2, v2
	v_xor_b32_e32 v2, 32, v11
	v_cmp_lt_i32_e32 vcc, v2, v3
	v_and_b32_e32 v3, 1, v10
	v_or3_b32 v6, v6, s1, v8
	v_cndmask_b32_e32 v2, v11, v2, vcc
	v_lshlrev_b32_e32 v199, 2, v2
	v_lshlrev_b32_e32 v2, 16, v10
	v_and_b32_e32 v2, 0xfffe0000, v2
	v_lshl_add_u32 v2, v12, 13, v2
	v_lshl_or_b32 v2, v3, 6, v2
	v_lshl_add_u32 v156, v13, 1, v2
	v_lshlrev_b32_e32 v2, 16, v14
	v_and_b32_e32 v2, 0xfffe0000, v2
	v_lshl_add_u32 v2, v15, 13, v2
	v_and_b32_e32 v3, 1, v14
	s_cselect_b64 s[28:29], -1, 0
	v_readlane_b32 s0, v255, 0
	v_lshl_or_b32 v2, v3, 6, v2
	s_add_i32 s77, 0, 0x10000
	s_add_i32 s78, 0, 0x14000
	v_cmp_gt_u32_e64 s[2:3], 16, v11
	s_ashr_i32 s73, s86, 31
	s_ashr_i32 s76, s0, 31
	v_mov_b32_e32 v157, v154
	v_lshl_add_u32 v158, v16, 1, v2
	v_mov_b32_e32 v159, v154
	v_mov_b64_e32 v[160:161], 0x400
	v_mov_b64_e32 v[162:163], 0x3ff
	v_add_u32_e32 v200, s77, v196
	v_add_u32_e32 v201, s78, v196
	v_add_u32_e32 v202, 0, v6
	v_mov_b32_e32 v203, 0x3727c5ac
	s_mov_b32 s79, 0xf800000
	v_mov_b32_e32 v204, 0x260
	s_mov_b32 s30, 0x3e6d3388
	s_mov_b32 s34, 0x3f07dc22
	s_mov_b32 s36, 0xbf3a00e3
	s_mov_b32 s38, 0x3f35f0e3
	s_mov_b32 s40, 0xbe11a98e
	s_mov_b32 s42, 0x3e027906
	s_mov_b32 s56, 0xbf38aa3b
	s_mov_b32 s80, 0x2f800000
	s_mov_b32 s81, 0xcf800000
	s_barrier
	s_branch .LBB0_1640

.LBB0_1911:
	v_readlane_b32 s8, v255, 48
	s_lshl_b32 s8, s8, 5
	s_and_b32 s49, s8, 0x60
	s_mov_b64 s[8:9], 0x80
	s_add_i32 m0, s19, 0x18000
	v_lshl_add_u64 v[8:9], v[8:9], 0, s[8:9]
	s_lshl_b32 s48, s3, 6
	s_lshl_b32 s3, s3, 13
	s_lshr_b32 s12, s49, 3
	global_load_lds_dwordx4 v[8:9], off
	v_lshl_add_u64 v[4:5], v[4:5], 0, s[8:9]
	s_add_i32 m0, s19, 0x1a000
	s_add_i32 s50, s19, 0x8000
	s_add_i32 s51, s19, 0xa000
	global_load_lds_dwordx4 v[4:5], off
	v_lshl_add_u64 v[2:3], v[2:3], 0, s[8:9]
	s_mov_b32 m0, s50
	s_add_u32 s10, s40, 0x100080
	global_load_lds_dwordx4 v[2:3], off
	v_lshl_add_u64 v[2:3], v[6:7], 0, s[8:9]
	s_mov_b32 m0, s51
	s_addc_u32 s11, s41, 0
	global_load_lds_dwordx4 v[2:3], off
	s_add_i32 m0, s19, 0x1c000
	v_lshl_add_u64 v[2:3], s[10:11], 0, v[172:173]
	global_load_lds_dwordx4 v[2:3], off
	v_lshl_add_u64 v[2:3], s[10:11], 0, v[176:177]
	s_add_i32 m0, s19, 0x1e000
	v_and_b32_e32 v210, 15, v12
	global_load_lds_dwordx4 v[2:3], off
	s_waitcnt vmcnt(8)
	s_barrier
	v_lshrrev_b32_e32 v2, 6, v12
	v_lshlrev_b32_e32 v6, 2, v12
	v_and_b32_e32 v3, 48, v12
	v_lshlrev_b32_e32 v4, 10, v2
	v_lshlrev_b32_e32 v5, 6, v210
	v_and_b32_e32 v6, 32, v6
	v_or_b32_e32 v2, s12, v2
	v_bitop3_b32 v7, v5, v6, v3 bitop3:0x36
	v_or_b32_e32 v3, v5, v3
	v_lshlrev_b32_e32 v2, 10, v2
	v_bitop3_b32 v211, v3, v2, v6 bitop3:0xde
	v_lshlrev_b32_e32 v2, 16, v10
	v_and_b32_e32 v2, 0xfffe0000, v2
	v_lshl_add_u32 v2, v11, 13, v2
	v_and_b32_e32 v3, 1, v10
	v_lshl_or_b32 v2, v3, 6, v2
	v_lshl_add_u32 v178, v13, 1, v2
	v_lshlrev_b32_e32 v2, 16, v14
	s_sext_i32_i8 s68, s2
	v_readlane_b32 s2, v255, 5
	v_and_b32_e32 v2, 0xfffe0000, v2
	s_waitcnt vmcnt(6)
	s_cmpk_lt_u32 s2, 0x100
	v_lshl_add_u32 v2, v15, 13, v2
	v_and_b32_e32 v3, 1, v14
	v_or3_b32 v4, v4, s3, v7
	s_cselect_b64 s[10:11], -1, 0
	v_lshl_or_b32 v2, v3, 6, v2
	s_add_i32 s57, 0, 0x10000
	s_add_i32 s60, 0, 0x14000
	v_lshrrev_b32_e32 v1, 4, v12
	s_ashr_i32 s56, s86, 31
	v_mov_b32_e32 v179, v173
	v_lshl_add_u32 v180, v16, 1, v2
	v_mov_b32_e32 v181, v173
	v_mov_b64_e32 v[182:183], 0x200
	v_mov_b64_e32 v[184:185], 0x1ff
	v_add_u32_e32 v212, s57, v211
	v_add_u32_e32 v213, s60, v211
	v_add_u32_e32 v214, 0, v4
	s_mov_b32 s61, 0x20000
	s_mov_b64 s[12:13], 0x40000
	s_mov_b32 s62, 0x40000
	s_mov_b64 s[14:15], 0x60000
	s_mov_b32 s63, 0x60000
	s_mov_b32 s64, 0x100000
	s_mov_b64 s[22:23], 0x120000
	s_mov_b32 s65, 0x120000
	s_mov_b64 s[24:25], 0x140000
	s_mov_b32 s66, 0x140000
	s_mov_b64 s[26:27], 0x160000
	s_mov_b32 s67, 0x160000
	s_barrier
	s_branch .LBB0_1914

.LBB0_2050:
	s_add_u32 s55, s64, 0x75000000
	s_addc_u32 s56, s65, 0
	s_add_u32 s57, s64, 0x75800000
	v_readlane_b32 s22, v255, 5
	s_mov_b64 s[14:15], 0x80
	s_addc_u32 s60, s65, 0
	s_bfe_u32 s24, s22, 0x20006
	s_add_i32 m0, s49, 0x18000
	v_lshl_add_u64 v[14:15], v[14:15], 0, s[14:15]
	s_lshl_b32 s61, s39, 6
	s_lshl_b32 s18, s39, 13
	s_lshl_b32 s62, s24, 5
	s_lshl_b32 s19, s24, 12
	global_load_lds_dwordx4 v[14:15], off
	v_lshl_add_u64 v[12:13], v[12:13], 0, s[14:15]
	s_add_i32 m0, s49, 0x1a000
	s_add_i32 s63, s49, 0x8000
	s_add_i32 s64, s49, 0xa000
	global_load_lds_dwordx4 v[12:13], off
	v_lshl_add_u64 v[10:11], v[10:11], 0, s[14:15]
	s_mov_b32 m0, s63
	s_add_u32 s16, s4, 0x80080
	global_load_lds_dwordx4 v[10:11], off
	v_lshl_add_u64 v[8:9], v[8:9], 0, s[14:15]
	s_mov_b32 m0, s64
	s_addc_u32 s17, s5, 0
	global_load_lds_dwordx4 v[8:9], off
	s_add_i32 m0, s49, 0x1c000
	v_lshl_add_u64 v[8:9], s[16:17], 0, v[144:145]
	global_load_lds_dwordx4 v[8:9], off
	v_lshl_add_u64 v[8:9], s[16:17], 0, v[148:149]
	s_add_i32 m0, s49, 0x1e000
	v_and_b32_e32 v230, 15, v16
	global_load_lds_dwordx4 v[8:9], off
	s_waitcnt vmcnt(8)
	s_barrier
	v_lshlrev_b32_e32 v11, 2, v16
	v_and_b32_e32 v8, 48, v16
	v_lshlrev_b32_e32 v10, 6, v230
	v_and_b32_e32 v11, 32, v11
	v_and_b32_e32 v9, 0x400, v24
	v_bitop3_b32 v8, v10, v11, v8 bitop3:0x36
	v_or3_b32 v10, v9, s18, v8
	v_or3_b32 v232, v9, s19, v8
	s_lshl_b32 s18, s39, 4
	s_lshl_b32 s19, s24, 2
	s_or_b32 s18, s19, s18
	s_lshl_b32 s71, s18, 3
	s_lshl_b32 s26, s18, 7
	s_or_b32 s65, s71, 8
	s_or_b32 s66, s71, 16
	s_or_b32 s67, s71, 24
	s_add_i32 s68, s71, 0x100
	s_add_i32 s69, s71, 0x108
	s_add_i32 s70, s71, 0x110
	s_addk_i32 s71, 0x118
	s_lshl_b32 s28, s24, 9
	s_cmpk_gt_u32 s22, 0xff
	s_cselect_b64 s[22:23], -1, 0
	s_cmp_lg_u32 s39, 1
	s_cselect_b64 s[18:19], -1, 0
	v_cndmask_b32_e64 v8, 0, 1, s[18:19]
	s_and_b64 s[18:19], s[18:19], exec
	s_cselect_b32 s19, 0, 2
	v_or_b32_e32 v8, s19, v8
	s_cselect_b32 s18, 0x800, 0
	v_lshlrev_b32_e32 v8, 11, v8
	s_add_i32 s77, 0, 0x20c00
	v_lshl_add_u64 v[150:151], v[2:3], 2, s[0:1]
	v_add_u32_e32 v2, s77, v8
	v_and_b32_e32 v3, 1, v17
	v_readlane_b32 s19, v255, 0
	v_add_u32_e32 v233, s28, v2
	v_add3_u32 v2, v19, v20, v21
	v_lshlrev_b32_e32 v3, 6, v3
	s_ashr_i32 s73, s19, 31
	s_lshl_b32 s19, s39, 8
	v_lshl_or_b32 v2, v2, 12, v3
	v_and_b32_e32 v3, 1, v22
	s_add_i32 s76, s19, 0
	v_lshl_add_u64 v[152:153], v[6:7], 0, v[4:5]
	v_lshl_add_u32 v4, v18, 1, v2
	v_add3_u32 v2, v25, v26, v27
	v_lshlrev_b32_e32 v3, 6, v3
	s_mov_b64 s[16:17], 0x80080
	s_ashr_i32 s72, s86, 31
	s_add_i32 s76, s76, 0x25400
	s_add_i32 s78, s77, s26
	s_lshl_b32 s19, s24, 7
	v_lshl_or_b32 v2, v2, 12, v3
	s_waitcnt vmcnt(6)
	s_add_u32 s79, s0, s19
	v_lshl_add_u64 v[154:155], v[4:5], 0, s[16:17]
	v_lshl_add_u32 v4, v23, 1, v2
	s_addc_u32 s80, s1, 0
	s_add_i32 s81, s77, s18
	v_lshl_add_u64 v[156:157], v[4:5], 0, s[16:17]
	s_add_i32 s82, 0, 0x10000
	s_add_i32 s16, 0, 0x14000
	v_lshrrev_b32_e32 v231, 4, v16
	s_mov_b32 s41, 0
	s_add_i32 s81, s81, s28
	v_mov_b64_e32 v[158:159], 0xe00
	v_mov_b64_e32 v[160:161], 0xdff
	v_add_u32_e32 v234, s82, v232
	v_add_u32_e32 v235, s16, v232
	v_add_u32_e32 v236, 0, v10
	s_mov_b32 s17, 0xe000
	v_mov_b32_e32 v237, 0x3727c5ac
	s_mov_b32 s83, 0xf800000
	v_mov_b32_e32 v238, 0x260
	s_mov_b32 s24, 0x3fb8aa3b
	s_mov_b32 s26, 0x3f317218
	s_movk_i32 s84, 0x7000
	s_barrier
	s_branch .LBB0_2053

.LBB0_2227:
	v_readlane_b32 s3, v255, 48
	s_lshl_b32 s3, s3, 5
	s_mov_b64 s[8:9], 0x80
	s_and_b32 s50, s3, 0x60
	s_add_i32 m0, s44, 0x18000
	v_lshl_add_u64 v[8:9], v[8:9], 0, s[8:9]
	s_lshl_b32 s49, s1, 6
	s_lshl_b32 s1, s1, 13
	s_lshr_b32 s3, s50, 3
	global_load_lds_dwordx4 v[8:9], off
	v_lshl_add_u64 v[6:7], v[6:7], 0, s[8:9]
	s_add_i32 m0, s44, 0x1a000
	s_add_i32 s51, s44, 0x8000
	s_add_i32 s54, s44, 0xa000
	global_load_lds_dwordx4 v[6:7], off
	v_lshl_add_u64 v[2:3], v[2:3], 0, s[8:9]
	s_mov_b32 m0, s51
	s_add_u32 s10, s36, 0x380080
	global_load_lds_dwordx4 v[2:3], off
	v_lshl_add_u64 v[2:3], v[4:5], 0, s[8:9]
	s_mov_b32 m0, s54
	s_addc_u32 s11, s37, 0
	global_load_lds_dwordx4 v[2:3], off
	s_add_i32 m0, s44, 0x1c000
	v_lshl_add_u64 v[2:3], s[10:11], 0, v[172:173]
	global_load_lds_dwordx4 v[2:3], off
	v_lshl_add_u64 v[2:3], s[10:11], 0, v[176:177]
	s_add_i32 m0, s44, 0x1e000
	v_and_b32_e32 v210, 15, v13
	global_load_lds_dwordx4 v[2:3], off
	s_waitcnt vmcnt(8)
	s_barrier
	v_lshlrev_b32_e32 v6, 2, v13
	v_lshrrev_b32_e32 v2, 6, v13
	v_and_b32_e32 v3, 48, v13
	v_lshlrev_b32_e32 v5, 6, v210
	v_and_b32_e32 v6, 32, v6
	v_lshlrev_b32_e32 v4, 10, v2
	v_bitop3_b32 v7, v5, v6, v3 bitop3:0x36
	v_or_b32_e32 v2, s3, v2
	v_or3_b32 v4, v4, s1, v7
	v_or_b32_e32 v3, v5, v3
	v_lshlrev_b32_e32 v2, 10, v2
	v_readlane_b32 s1, v255, 5
	v_bitop3_b32 v211, v3, v2, v6 bitop3:0xde
	s_cmpk_lt_u32 s1, 0x100
	v_lshrrev_b32_e32 v3, 1, v10
	v_mul_lo_u32 v2, v12, s0
	s_mov_b32 s1, 0x38000
	v_mad_u64_u32 v[2:3], s[12:13], v3, s1, v[2:3]
	v_or_b32_e32 v2, v2, v11
	s_sext_i32_i8 s68, s2
	s_mov_b64 s[2:3], 0x380080
	v_add_lshl_u32 v2, v2, v14, 1
	v_mov_b32_e32 v3, v173
	v_lshl_add_u64 v[178:179], v[2:3], 0, s[2:3]
	v_lshrrev_b32_e32 v3, 1, v15
	v_mul_lo_u32 v2, v16, s0
	v_mad_u64_u32 v[2:3], s[0:1], v3, s1, v[2:3]
	s_waitcnt vmcnt(6)
	v_or_b32_e32 v2, v2, v17
	s_cselect_b64 s[10:11], -1, 0
	v_add_lshl_u32 v2, v2, v18, 1
	v_mov_b32_e32 v3, v173
	s_add_i32 s56, 0, 0x10000
	s_add_i32 s57, 0, 0x14000
	v_lshrrev_b32_e32 v1, 4, v13
	s_ashr_i32 s55, s86, 31
	v_lshl_add_u64 v[180:181], v[2:3], 0, s[2:3]
	v_mov_b64_e32 v[182:183], 0x200
	v_mov_b64_e32 v[184:185], 0x1ff
	v_add_u32_e32 v212, s56, v211
	v_add_u32_e32 v213, s57, v211
	v_add_u32_e32 v214, 0, v4
	s_mov_b64 s[12:13], 0x20000
	s_mov_b32 s58, 0x20000
	s_mov_b64 s[14:15], 0x40000
	s_mov_b32 s59, 0x40000
	s_mov_b64 s[22:23], 0x60000
	s_mov_b32 s60, 0x60000
	s_mov_b64 s[24:25], 0x100000
	s_mov_b32 s61, 0x100000
	s_mov_b64 s[26:27], 0x120000
	s_mov_b32 s62, 0x120000
	s_mov_b64 s[28:29], 0x140000
	s_mov_b32 s63, 0x140000
	s_mov_b64 s[30:31], 0x160000
	s_mov_b32 s64, 0x160000
	s_barrier
	s_branch .LBB0_2230
